# P0 pooled out-projection weights step hand-rewritten: one wave per (g, 64 n, 4 c) task with double-buffered loads
# speedup vs baseline: 1.0317x; 1.0016x over previous
; __device__ __forceinline__ bf16_t f2bf(float x) { unsigned u = __float_as_uint(x); u += 0x7fffu + ((u >> 16) & 1u); return (bf16_t)(u >> 16); }
; __device__ __forceinline__ void p0_prologue(const Params& p, LAS unsigned char* lds, const int wave_s) {
;     ...
;     for (int o = gt; o < 128 * 1024; o += GT) {
;         const int n = o & 1023, c = o >> 10;
;         const float* wo = p.in[I_WOUT] + (size_t)512 * 1024 + n;
;         float a0 = 0.f, a1 = 0.f, a2 = 0.f, a3 = 0.f;
;         const float* wp = p.in[I_WPOOL] + (size_t)c * 128; const float* ps = p.in[I_PSCALE];
; #pragma unroll 8
;         for (int e = 0; e < 128; ++e) {
;             a0 += wp[e] * ps[e] * wo[(size_t)e * 1024];
;             a1 += wp[16384 + e] * ps[128 + e] * wo[(size_t)(128 + e) * 1024];
;             a2 += wp[32768 + e] * ps[256 + e] * wo[(size_t)(256 + e) * 1024];
;             a3 += wp[49152 + e] * ps[384 + e] * wo[(size_t)(384 + e) * 1024];
;         }
;         bf16_t* dst = WOUT + (size_t)n * 1024 + 512 + c;
;         dst[0] = f2bf(a0); dst[128] = f2bf(a1); dst[256] = f2bf(a2); dst[384] = f2bf(a3);
;     }
.LBB0_180:
	s_lshl_b32 s70, s93, 9
	v_add_u32_e32 v44, s70, v1
	s_mov_b32 s23, 0x20000
	s_lshl_b32 s22, s82, 9
	v_cmp_gt_i32_e64 s[0:1], s23, v44
	s_and_saveexec_b64 s[2:3], s[0:1]
	s_cbranch_execz .LBB0_185
	s_waitcnt lgkmcnt(0)
	s_lshr_b32 s4, s90, 6
	s_lshl_b32 s26, s93, 3
	s_add_i32 s26, s26, s4
	s_lshl_b32 s27, s82, 3
	v_mov_b32_e32 v4, 0
.Lpw_task:
	s_cmpk_gt_u32 s26, 0x7ff
	s_cbranch_scc1 .Lpw_done
	s_and_b32 s4, s26, 3
	s_bfe_u32 s5, s26, 0x40002
	s_lshr_b32 s24, s26, 6
	s_lshl_b32 s25, s5, 6
	v_add_u32_e32 v2, s25, v42
	s_lshl_b32 s28, s4, 7
	s_lshl_b32 s29, s24, 2
	s_add_i32 s30, s28, s29
	s_addk_i32 s30, 0x200
	v_lshlrev_b32_e32 v3, 11, v2
	s_lshl_b32 s30, s30, 1
	v_add_u32_e32 v3, s30, v3
	v_lshlrev_b32_e32 v2, 2, v2
	s_addk_i32 s28, 0x200
	s_lshl_b32 s31, s28, 12
	s_add_u32 s8, s66, s31
	s_addc_u32 s9, s67, 0
	s_lshl_b32 s31, s4, 16
	s_lshl_b32 s34, s29, 9
	s_add_i32 s31, s31, s34
	s_add_u32 s10, s62, s31
	s_addc_u32 s11, s63, 0
	s_addk_i32 s31, 0x200
	s_add_u32 s12, s62, s31
	s_addc_u32 s13, s63, 0
	s_addk_i32 s31, 0x200
	s_add_u32 s14, s62, s31
	s_addc_u32 s15, s63, 0
	s_addk_i32 s31, 0x200
	s_add_u32 s16, s62, s31
	s_addc_u32 s17, s63, 0
	s_lshl_b32 s31, s4, 9
	s_add_u32 s20, s64, s31
	s_addc_u32 s21, s65, 0
	v_mov_b32_e32 v5, 0
	v_mov_b32_e32 v6, 0
	v_mov_b32_e32 v7, 0
	v_mov_b32_e32 v8, 0
	s_nop 3
	global_load_dword v12, v2, s[8:9]
	s_add_u32 s8, s8, 0x1000
	s_addc_u32 s9, s9, 0
	global_load_dword v13, v2, s[8:9]
	s_add_u32 s8, s8, 0x1000
	s_addc_u32 s9, s9, 0
	global_load_dword v14, v2, s[8:9]
	s_add_u32 s8, s8, 0x1000
	s_addc_u32 s9, s9, 0
	global_load_dword v15, v2, s[8:9]
	s_add_u32 s8, s8, 0x1000
	s_addc_u32 s9, s9, 0
	global_load_dword v16, v2, s[8:9]
	s_add_u32 s8, s8, 0x1000
	s_addc_u32 s9, s9, 0
	global_load_dword v17, v2, s[8:9]
	s_add_u32 s8, s8, 0x1000
	s_addc_u32 s9, s9, 0
	global_load_dword v18, v2, s[8:9]
	s_add_u32 s8, s8, 0x1000
	s_addc_u32 s9, s9, 0
	global_load_dword v19, v2, s[8:9]
	s_add_u32 s8, s8, 0x1000
	s_addc_u32 s9, s9, 0
	global_load_dwordx4 v[20:23], v4, s[10:11] offset:0
	global_load_dwordx4 v[24:27], v4, s[10:11] offset:16
	global_load_dwordx4 v[28:31], v4, s[12:13] offset:0
	global_load_dwordx4 v[32:35], v4, s[12:13] offset:16
	global_load_dwordx4 v[54:57], v4, s[14:15] offset:0
	global_load_dwordx4 v[58:61], v4, s[14:15] offset:16
	global_load_dwordx4 v[62:65], v4, s[16:17] offset:0
	global_load_dwordx4 v[66:69], v4, s[16:17] offset:16
	global_load_dwordx4 v[70:73], v4, s[20:21] offset:0
	global_load_dwordx4 v[74:77], v4, s[20:21] offset:16
	global_load_dword v78, v2, s[8:9]
	s_add_u32 s8, s8, 0x1000
	s_addc_u32 s9, s9, 0
	global_load_dword v79, v2, s[8:9]
	s_add_u32 s8, s8, 0x1000
	s_addc_u32 s9, s9, 0
	global_load_dword v80, v2, s[8:9]
	s_add_u32 s8, s8, 0x1000
	s_addc_u32 s9, s9, 0
	global_load_dword v81, v2, s[8:9]
	s_add_u32 s8, s8, 0x1000
	s_addc_u32 s9, s9, 0
	global_load_dword v82, v2, s[8:9]
	s_add_u32 s8, s8, 0x1000
	s_addc_u32 s9, s9, 0
	global_load_dword v83, v2, s[8:9]
	s_add_u32 s8, s8, 0x1000
	s_addc_u32 s9, s9, 0
	global_load_dword v84, v2, s[8:9]
	s_add_u32 s8, s8, 0x1000
	s_addc_u32 s9, s9, 0
	global_load_dword v85, v2, s[8:9]
	s_add_u32 s8, s8, 0x1000
	s_addc_u32 s9, s9, 0
	global_load_dwordx4 v[86:89], v4, s[10:11] offset:32
	global_load_dwordx4 v[90:93], v4, s[10:11] offset:48
	global_load_dwordx4 v[94:97], v4, s[12:13] offset:32
	global_load_dwordx4 v[98:101], v4, s[12:13] offset:48
	global_load_dwordx4 v[102:105], v4, s[14:15] offset:32
	global_load_dwordx4 v[106:109], v4, s[14:15] offset:48
	global_load_dwordx4 v[110:113], v4, s[16:17] offset:32
	global_load_dwordx4 v[114:117], v4, s[16:17] offset:48
	global_load_dwordx4 v[118:121], v4, s[20:21] offset:32
	global_load_dwordx4 v[122:125], v4, s[20:21] offset:48
	s_waitcnt vmcnt(18)
	v_mul_f32_e32 v9, v20, v70
	v_fmac_f32_e32 v5, v9, v12
	v_mul_f32_e32 v9, v28, v70
	v_fmac_f32_e32 v6, v9, v12
	v_mul_f32_e32 v9, v54, v70
	v_fmac_f32_e32 v7, v9, v12
	v_mul_f32_e32 v9, v62, v70
	v_fmac_f32_e32 v8, v9, v12
	v_mul_f32_e32 v9, v21, v71
	v_fmac_f32_e32 v5, v9, v13
	v_mul_f32_e32 v9, v29, v71
	v_fmac_f32_e32 v6, v9, v13
	v_mul_f32_e32 v9, v55, v71
	v_fmac_f32_e32 v7, v9, v13
	v_mul_f32_e32 v9, v63, v71
	v_fmac_f32_e32 v8, v9, v13
	v_mul_f32_e32 v9, v22, v72
	v_fmac_f32_e32 v5, v9, v14
	v_mul_f32_e32 v9, v30, v72
	v_fmac_f32_e32 v6, v9, v14
	v_mul_f32_e32 v9, v56, v72
	v_fmac_f32_e32 v7, v9, v14
	v_mul_f32_e32 v9, v64, v72
	v_fmac_f32_e32 v8, v9, v14
	v_mul_f32_e32 v9, v23, v73
	v_fmac_f32_e32 v5, v9, v15
	v_mul_f32_e32 v9, v31, v73
	v_fmac_f32_e32 v6, v9, v15
	v_mul_f32_e32 v9, v57, v73
	v_fmac_f32_e32 v7, v9, v15
	v_mul_f32_e32 v9, v65, v73
	v_fmac_f32_e32 v8, v9, v15
	v_mul_f32_e32 v9, v24, v74
	v_fmac_f32_e32 v5, v9, v16
	v_mul_f32_e32 v9, v32, v74
	v_fmac_f32_e32 v6, v9, v16
	v_mul_f32_e32 v9, v58, v74
	v_fmac_f32_e32 v7, v9, v16
	v_mul_f32_e32 v9, v66, v74
	v_fmac_f32_e32 v8, v9, v16
	v_mul_f32_e32 v9, v25, v75
	v_fmac_f32_e32 v5, v9, v17
	v_mul_f32_e32 v9, v33, v75
	v_fmac_f32_e32 v6, v9, v17
	v_mul_f32_e32 v9, v59, v75
	v_fmac_f32_e32 v7, v9, v17
	v_mul_f32_e32 v9, v67, v75
	v_fmac_f32_e32 v8, v9, v17
	v_mul_f32_e32 v9, v26, v76
	v_fmac_f32_e32 v5, v9, v18
	v_mul_f32_e32 v9, v34, v76
	v_fmac_f32_e32 v6, v9, v18
	v_mul_f32_e32 v9, v60, v76
	v_fmac_f32_e32 v7, v9, v18
	v_mul_f32_e32 v9, v68, v76
	v_fmac_f32_e32 v8, v9, v18
	v_mul_f32_e32 v9, v27, v77
	v_fmac_f32_e32 v5, v9, v19
	v_mul_f32_e32 v9, v35, v77
	v_fmac_f32_e32 v6, v9, v19
	v_mul_f32_e32 v9, v61, v77
	v_fmac_f32_e32 v7, v9, v19
	v_mul_f32_e32 v9, v69, v77
	v_fmac_f32_e32 v8, v9, v19
	global_load_dword v12, v2, s[8:9]
	s_add_u32 s8, s8, 0x1000
	s_addc_u32 s9, s9, 0
	global_load_dword v13, v2, s[8:9]
	s_add_u32 s8, s8, 0x1000
	s_addc_u32 s9, s9, 0
	global_load_dword v14, v2, s[8:9]
	s_add_u32 s8, s8, 0x1000
	s_addc_u32 s9, s9, 0
	global_load_dword v15, v2, s[8:9]
	s_add_u32 s8, s8, 0x1000
	s_addc_u32 s9, s9, 0
	global_load_dword v16, v2, s[8:9]
	s_add_u32 s8, s8, 0x1000
	s_addc_u32 s9, s9, 0
	global_load_dword v17, v2, s[8:9]
	s_add_u32 s8, s8, 0x1000
	s_addc_u32 s9, s9, 0
	global_load_dword v18, v2, s[8:9]
	s_add_u32 s8, s8, 0x1000
	s_addc_u32 s9, s9, 0
	global_load_dword v19, v2, s[8:9]
	s_add_u32 s8, s8, 0x1000
	s_addc_u32 s9, s9, 0
	global_load_dwordx4 v[20:23], v4, s[10:11] offset:64
	global_load_dwordx4 v[24:27], v4, s[10:11] offset:80
	global_load_dwordx4 v[28:31], v4, s[12:13] offset:64
	global_load_dwordx4 v[32:35], v4, s[12:13] offset:80
	global_load_dwordx4 v[54:57], v4, s[14:15] offset:64
	global_load_dwordx4 v[58:61], v4, s[14:15] offset:80
	global_load_dwordx4 v[62:65], v4, s[16:17] offset:64
	global_load_dwordx4 v[66:69], v4, s[16:17] offset:80
	global_load_dwordx4 v[70:73], v4, s[20:21] offset:64
	global_load_dwordx4 v[74:77], v4, s[20:21] offset:80
	s_waitcnt vmcnt(18)
; __device__ __forceinline__ void p0_prologue(const Params& p, LAS unsigned char* lds, const int wave_s) {
;     ...
;         for (int e = 0; e < 128; ++e) {
;             a0 += wp[e] * ps[e] * wo[(size_t)e * 1024];
;             a1 += wp[16384 + e] * ps[128 + e] * wo[(size_t)(128 + e) * 1024];
;             a2 += wp[32768 + e] * ps[256 + e] * wo[(size_t)(256 + e) * 1024];
;             a3 += wp[49152 + e] * ps[384 + e] * wo[(size_t)(384 + e) * 1024];
;         }
	v_mul_f32_e32 v9, v86, v118
	v_fmac_f32_e32 v5, v9, v78
	v_mul_f32_e32 v9, v94, v118
	v_fmac_f32_e32 v6, v9, v78
	v_mul_f32_e32 v9, v102, v118
	v_fmac_f32_e32 v7, v9, v78
	v_mul_f32_e32 v9, v110, v118
	v_fmac_f32_e32 v8, v9, v78
	v_mul_f32_e32 v9, v87, v119
	v_fmac_f32_e32 v5, v9, v79
	v_mul_f32_e32 v9, v95, v119
	v_fmac_f32_e32 v6, v9, v79
	v_mul_f32_e32 v9, v103, v119
	v_fmac_f32_e32 v7, v9, v79
	v_mul_f32_e32 v9, v111, v119
	v_fmac_f32_e32 v8, v9, v79
	v_mul_f32_e32 v9, v88, v120
	v_fmac_f32_e32 v5, v9, v80
	v_mul_f32_e32 v9, v96, v120
	v_fmac_f32_e32 v6, v9, v80
	v_mul_f32_e32 v9, v104, v120
	v_fmac_f32_e32 v7, v9, v80
	v_mul_f32_e32 v9, v112, v120
	v_fmac_f32_e32 v8, v9, v80
	v_mul_f32_e32 v9, v89, v121
	v_fmac_f32_e32 v5, v9, v81
	v_mul_f32_e32 v9, v97, v121
	v_fmac_f32_e32 v6, v9, v81
	v_mul_f32_e32 v9, v105, v121
	v_fmac_f32_e32 v7, v9, v81
	v_mul_f32_e32 v9, v113, v121
	v_fmac_f32_e32 v8, v9, v81
	v_mul_f32_e32 v9, v90, v122
	v_fmac_f32_e32 v5, v9, v82
	v_mul_f32_e32 v9, v98, v122
	v_fmac_f32_e32 v6, v9, v82
	v_mul_f32_e32 v9, v106, v122
	v_fmac_f32_e32 v7, v9, v82
	v_mul_f32_e32 v9, v114, v122
	v_fmac_f32_e32 v8, v9, v82
	v_mul_f32_e32 v9, v91, v123
	v_fmac_f32_e32 v5, v9, v83
	v_mul_f32_e32 v9, v99, v123
	v_fmac_f32_e32 v6, v9, v83
	v_mul_f32_e32 v9, v107, v123
	v_fmac_f32_e32 v7, v9, v83
	v_mul_f32_e32 v9, v115, v123
	v_fmac_f32_e32 v8, v9, v83
	v_mul_f32_e32 v9, v92, v124
	v_fmac_f32_e32 v5, v9, v84
	v_mul_f32_e32 v9, v100, v124
	v_fmac_f32_e32 v6, v9, v84
	v_mul_f32_e32 v9, v108, v124
	v_fmac_f32_e32 v7, v9, v84
	v_mul_f32_e32 v9, v116, v124
	v_fmac_f32_e32 v8, v9, v84
	v_mul_f32_e32 v9, v93, v125
	v_fmac_f32_e32 v5, v9, v85
	v_mul_f32_e32 v9, v101, v125
	v_fmac_f32_e32 v6, v9, v85
	v_mul_f32_e32 v9, v109, v125
	v_fmac_f32_e32 v7, v9, v85
	v_mul_f32_e32 v9, v117, v125
	v_fmac_f32_e32 v8, v9, v85
	global_load_dword v78, v2, s[8:9]
	s_add_u32 s8, s8, 0x1000
	s_addc_u32 s9, s9, 0
	global_load_dword v79, v2, s[8:9]
	s_add_u32 s8, s8, 0x1000
	s_addc_u32 s9, s9, 0
	global_load_dword v80, v2, s[8:9]
	s_add_u32 s8, s8, 0x1000
	s_addc_u32 s9, s9, 0
	global_load_dword v81, v2, s[8:9]
	s_add_u32 s8, s8, 0x1000
	s_addc_u32 s9, s9, 0
	global_load_dword v82, v2, s[8:9]
	s_add_u32 s8, s8, 0x1000
	s_addc_u32 s9, s9, 0
	global_load_dword v83, v2, s[8:9]
	s_add_u32 s8, s8, 0x1000
	s_addc_u32 s9, s9, 0
	global_load_dword v84, v2, s[8:9]
	s_add_u32 s8, s8, 0x1000
	s_addc_u32 s9, s9, 0
	global_load_dword v85, v2, s[8:9]
	s_add_u32 s8, s8, 0x1000
	s_addc_u32 s9, s9, 0
	global_load_dwordx4 v[86:89], v4, s[10:11] offset:96
	global_load_dwordx4 v[90:93], v4, s[10:11] offset:112
	global_load_dwordx4 v[94:97], v4, s[12:13] offset:96
	global_load_dwordx4 v[98:101], v4, s[12:13] offset:112
	global_load_dwordx4 v[102:105], v4, s[14:15] offset:96
	global_load_dwordx4 v[106:109], v4, s[14:15] offset:112
	global_load_dwordx4 v[110:113], v4, s[16:17] offset:96
	global_load_dwordx4 v[114:117], v4, s[16:17] offset:112
	global_load_dwordx4 v[118:121], v4, s[20:21] offset:96
	global_load_dwordx4 v[122:125], v4, s[20:21] offset:112
	s_waitcnt vmcnt(18)
	v_mul_f32_e32 v9, v20, v70
	v_fmac_f32_e32 v5, v9, v12
	v_mul_f32_e32 v9, v28, v70
	v_fmac_f32_e32 v6, v9, v12
	v_mul_f32_e32 v9, v54, v70
	v_fmac_f32_e32 v7, v9, v12
	v_mul_f32_e32 v9, v62, v70
	v_fmac_f32_e32 v8, v9, v12
	v_mul_f32_e32 v9, v21, v71
	v_fmac_f32_e32 v5, v9, v13
	v_mul_f32_e32 v9, v29, v71
	v_fmac_f32_e32 v6, v9, v13
	v_mul_f32_e32 v9, v55, v71
	v_fmac_f32_e32 v7, v9, v13
	v_mul_f32_e32 v9, v63, v71
	v_fmac_f32_e32 v8, v9, v13
	v_mul_f32_e32 v9, v22, v72
	v_fmac_f32_e32 v5, v9, v14
	v_mul_f32_e32 v9, v30, v72
	v_fmac_f32_e32 v6, v9, v14
	v_mul_f32_e32 v9, v56, v72
	v_fmac_f32_e32 v7, v9, v14
	v_mul_f32_e32 v9, v64, v72
	v_fmac_f32_e32 v8, v9, v14
	v_mul_f32_e32 v9, v23, v73
	v_fmac_f32_e32 v5, v9, v15
	v_mul_f32_e32 v9, v31, v73
	v_fmac_f32_e32 v6, v9, v15
	v_mul_f32_e32 v9, v57, v73
	v_fmac_f32_e32 v7, v9, v15
	v_mul_f32_e32 v9, v65, v73
	v_fmac_f32_e32 v8, v9, v15
	v_mul_f32_e32 v9, v24, v74
	v_fmac_f32_e32 v5, v9, v16
	v_mul_f32_e32 v9, v32, v74
	v_fmac_f32_e32 v6, v9, v16
	v_mul_f32_e32 v9, v58, v74
	v_fmac_f32_e32 v7, v9, v16
	v_mul_f32_e32 v9, v66, v74
	v_fmac_f32_e32 v8, v9, v16
	v_mul_f32_e32 v9, v25, v75
	v_fmac_f32_e32 v5, v9, v17
	v_mul_f32_e32 v9, v33, v75
	v_fmac_f32_e32 v6, v9, v17
	v_mul_f32_e32 v9, v59, v75
	v_fmac_f32_e32 v7, v9, v17
	v_mul_f32_e32 v9, v67, v75
	v_fmac_f32_e32 v8, v9, v17
	v_mul_f32_e32 v9, v26, v76
	v_fmac_f32_e32 v5, v9, v18
	v_mul_f32_e32 v9, v34, v76
	v_fmac_f32_e32 v6, v9, v18
	v_mul_f32_e32 v9, v60, v76
	v_fmac_f32_e32 v7, v9, v18
	v_mul_f32_e32 v9, v68, v76
	v_fmac_f32_e32 v8, v9, v18
	v_mul_f32_e32 v9, v27, v77
	v_fmac_f32_e32 v5, v9, v19
	v_mul_f32_e32 v9, v35, v77
	v_fmac_f32_e32 v6, v9, v19
	v_mul_f32_e32 v9, v61, v77
	v_fmac_f32_e32 v7, v9, v19
	v_mul_f32_e32 v9, v69, v77
	v_fmac_f32_e32 v8, v9, v19
	global_load_dword v12, v2, s[8:9]
	s_add_u32 s8, s8, 0x1000
	s_addc_u32 s9, s9, 0
	global_load_dword v13, v2, s[8:9]
	s_add_u32 s8, s8, 0x1000
	s_addc_u32 s9, s9, 0
	global_load_dword v14, v2, s[8:9]
	s_add_u32 s8, s8, 0x1000
	s_addc_u32 s9, s9, 0
	global_load_dword v15, v2, s[8:9]
	s_add_u32 s8, s8, 0x1000
	s_addc_u32 s9, s9, 0
	global_load_dword v16, v2, s[8:9]
	s_add_u32 s8, s8, 0x1000
	s_addc_u32 s9, s9, 0
	global_load_dword v17, v2, s[8:9]
	s_add_u32 s8, s8, 0x1000
	s_addc_u32 s9, s9, 0
	global_load_dword v18, v2, s[8:9]
	s_add_u32 s8, s8, 0x1000
	s_addc_u32 s9, s9, 0
	global_load_dword v19, v2, s[8:9]
	s_add_u32 s8, s8, 0x1000
	s_addc_u32 s9, s9, 0
	global_load_dwordx4 v[20:23], v4, s[10:11] offset:128
	global_load_dwordx4 v[24:27], v4, s[10:11] offset:144
	global_load_dwordx4 v[28:31], v4, s[12:13] offset:128
	global_load_dwordx4 v[32:35], v4, s[12:13] offset:144
	global_load_dwordx4 v[54:57], v4, s[14:15] offset:128
	global_load_dwordx4 v[58:61], v4, s[14:15] offset:144
	global_load_dwordx4 v[62:65], v4, s[16:17] offset:128
	global_load_dwordx4 v[66:69], v4, s[16:17] offset:144
	global_load_dwordx4 v[70:73], v4, s[20:21] offset:128
	global_load_dwordx4 v[74:77], v4, s[20:21] offset:144
	s_waitcnt vmcnt(18)
; __device__ __forceinline__ void p0_prologue(const Params& p, LAS unsigned char* lds, const int wave_s) {
;     ...
;         for (int e = 0; e < 128; ++e) {
;             a0 += wp[e] * ps[e] * wo[(size_t)e * 1024];
;             a1 += wp[16384 + e] * ps[128 + e] * wo[(size_t)(128 + e) * 1024];
;             a2 += wp[32768 + e] * ps[256 + e] * wo[(size_t)(256 + e) * 1024];
;             a3 += wp[49152 + e] * ps[384 + e] * wo[(size_t)(384 + e) * 1024];
;         }
	v_mul_f32_e32 v9, v86, v118
	v_fmac_f32_e32 v5, v9, v78
	v_mul_f32_e32 v9, v94, v118
	v_fmac_f32_e32 v6, v9, v78
	v_mul_f32_e32 v9, v102, v118
	v_fmac_f32_e32 v7, v9, v78
	v_mul_f32_e32 v9, v110, v118
	v_fmac_f32_e32 v8, v9, v78
	v_mul_f32_e32 v9, v87, v119
	v_fmac_f32_e32 v5, v9, v79
	v_mul_f32_e32 v9, v95, v119
	v_fmac_f32_e32 v6, v9, v79
	v_mul_f32_e32 v9, v103, v119
	v_fmac_f32_e32 v7, v9, v79
	v_mul_f32_e32 v9, v111, v119
	v_fmac_f32_e32 v8, v9, v79
	v_mul_f32_e32 v9, v88, v120
	v_fmac_f32_e32 v5, v9, v80
	v_mul_f32_e32 v9, v96, v120
	v_fmac_f32_e32 v6, v9, v80
	v_mul_f32_e32 v9, v104, v120
	v_fmac_f32_e32 v7, v9, v80
	v_mul_f32_e32 v9, v112, v120
	v_fmac_f32_e32 v8, v9, v80
	v_mul_f32_e32 v9, v89, v121
	v_fmac_f32_e32 v5, v9, v81
	v_mul_f32_e32 v9, v97, v121
	v_fmac_f32_e32 v6, v9, v81
	v_mul_f32_e32 v9, v105, v121
	v_fmac_f32_e32 v7, v9, v81
	v_mul_f32_e32 v9, v113, v121
	v_fmac_f32_e32 v8, v9, v81
	v_mul_f32_e32 v9, v90, v122
	v_fmac_f32_e32 v5, v9, v82
	v_mul_f32_e32 v9, v98, v122
	v_fmac_f32_e32 v6, v9, v82
	v_mul_f32_e32 v9, v106, v122
	v_fmac_f32_e32 v7, v9, v82
	v_mul_f32_e32 v9, v114, v122
	v_fmac_f32_e32 v8, v9, v82
	v_mul_f32_e32 v9, v91, v123
	v_fmac_f32_e32 v5, v9, v83
	v_mul_f32_e32 v9, v99, v123
	v_fmac_f32_e32 v6, v9, v83
	v_mul_f32_e32 v9, v107, v123
	v_fmac_f32_e32 v7, v9, v83
	v_mul_f32_e32 v9, v115, v123
	v_fmac_f32_e32 v8, v9, v83
	v_mul_f32_e32 v9, v92, v124
	v_fmac_f32_e32 v5, v9, v84
	v_mul_f32_e32 v9, v100, v124
	v_fmac_f32_e32 v6, v9, v84
	v_mul_f32_e32 v9, v108, v124
	v_fmac_f32_e32 v7, v9, v84
	v_mul_f32_e32 v9, v116, v124
	v_fmac_f32_e32 v8, v9, v84
	v_mul_f32_e32 v9, v93, v125
	v_fmac_f32_e32 v5, v9, v85
	v_mul_f32_e32 v9, v101, v125
	v_fmac_f32_e32 v6, v9, v85
	v_mul_f32_e32 v9, v109, v125
	v_fmac_f32_e32 v7, v9, v85
	v_mul_f32_e32 v9, v117, v125
	v_fmac_f32_e32 v8, v9, v85
	global_load_dword v78, v2, s[8:9]
	s_add_u32 s8, s8, 0x1000
	s_addc_u32 s9, s9, 0
	global_load_dword v79, v2, s[8:9]
	s_add_u32 s8, s8, 0x1000
	s_addc_u32 s9, s9, 0
	global_load_dword v80, v2, s[8:9]
	s_add_u32 s8, s8, 0x1000
	s_addc_u32 s9, s9, 0
	global_load_dword v81, v2, s[8:9]
	s_add_u32 s8, s8, 0x1000
	s_addc_u32 s9, s9, 0
	global_load_dword v82, v2, s[8:9]
	s_add_u32 s8, s8, 0x1000
	s_addc_u32 s9, s9, 0
	global_load_dword v83, v2, s[8:9]
	s_add_u32 s8, s8, 0x1000
	s_addc_u32 s9, s9, 0
	global_load_dword v84, v2, s[8:9]
	s_add_u32 s8, s8, 0x1000
	s_addc_u32 s9, s9, 0
	global_load_dword v85, v2, s[8:9]
	s_add_u32 s8, s8, 0x1000
	s_addc_u32 s9, s9, 0
	global_load_dwordx4 v[86:89], v4, s[10:11] offset:160
	global_load_dwordx4 v[90:93], v4, s[10:11] offset:176
	global_load_dwordx4 v[94:97], v4, s[12:13] offset:160
	global_load_dwordx4 v[98:101], v4, s[12:13] offset:176
	global_load_dwordx4 v[102:105], v4, s[14:15] offset:160
	global_load_dwordx4 v[106:109], v4, s[14:15] offset:176
	global_load_dwordx4 v[110:113], v4, s[16:17] offset:160
	global_load_dwordx4 v[114:117], v4, s[16:17] offset:176
	global_load_dwordx4 v[118:121], v4, s[20:21] offset:160
	global_load_dwordx4 v[122:125], v4, s[20:21] offset:176
	s_waitcnt vmcnt(18)
	v_mul_f32_e32 v9, v20, v70
	v_fmac_f32_e32 v5, v9, v12
	v_mul_f32_e32 v9, v28, v70
	v_fmac_f32_e32 v6, v9, v12
	v_mul_f32_e32 v9, v54, v70
	v_fmac_f32_e32 v7, v9, v12
	v_mul_f32_e32 v9, v62, v70
	v_fmac_f32_e32 v8, v9, v12
	v_mul_f32_e32 v9, v21, v71
	v_fmac_f32_e32 v5, v9, v13
	v_mul_f32_e32 v9, v29, v71
	v_fmac_f32_e32 v6, v9, v13
	v_mul_f32_e32 v9, v55, v71
	v_fmac_f32_e32 v7, v9, v13
	v_mul_f32_e32 v9, v63, v71
	v_fmac_f32_e32 v8, v9, v13
	v_mul_f32_e32 v9, v22, v72
	v_fmac_f32_e32 v5, v9, v14
	v_mul_f32_e32 v9, v30, v72
	v_fmac_f32_e32 v6, v9, v14
	v_mul_f32_e32 v9, v56, v72
	v_fmac_f32_e32 v7, v9, v14
	v_mul_f32_e32 v9, v64, v72
	v_fmac_f32_e32 v8, v9, v14
	v_mul_f32_e32 v9, v23, v73
	v_fmac_f32_e32 v5, v9, v15
	v_mul_f32_e32 v9, v31, v73
	v_fmac_f32_e32 v6, v9, v15
	v_mul_f32_e32 v9, v57, v73
	v_fmac_f32_e32 v7, v9, v15
	v_mul_f32_e32 v9, v65, v73
	v_fmac_f32_e32 v8, v9, v15
	v_mul_f32_e32 v9, v24, v74
	v_fmac_f32_e32 v5, v9, v16
	v_mul_f32_e32 v9, v32, v74
	v_fmac_f32_e32 v6, v9, v16
	v_mul_f32_e32 v9, v58, v74
	v_fmac_f32_e32 v7, v9, v16
	v_mul_f32_e32 v9, v66, v74
	v_fmac_f32_e32 v8, v9, v16
	v_mul_f32_e32 v9, v25, v75
	v_fmac_f32_e32 v5, v9, v17
	v_mul_f32_e32 v9, v33, v75
	v_fmac_f32_e32 v6, v9, v17
	v_mul_f32_e32 v9, v59, v75
	v_fmac_f32_e32 v7, v9, v17
	v_mul_f32_e32 v9, v67, v75
	v_fmac_f32_e32 v8, v9, v17
	v_mul_f32_e32 v9, v26, v76
	v_fmac_f32_e32 v5, v9, v18
	v_mul_f32_e32 v9, v34, v76
	v_fmac_f32_e32 v6, v9, v18
	v_mul_f32_e32 v9, v60, v76
	v_fmac_f32_e32 v7, v9, v18
	v_mul_f32_e32 v9, v68, v76
	v_fmac_f32_e32 v8, v9, v18
	v_mul_f32_e32 v9, v27, v77
	v_fmac_f32_e32 v5, v9, v19
	v_mul_f32_e32 v9, v35, v77
	v_fmac_f32_e32 v6, v9, v19
	v_mul_f32_e32 v9, v61, v77
	v_fmac_f32_e32 v7, v9, v19
	v_mul_f32_e32 v9, v69, v77
	v_fmac_f32_e32 v8, v9, v19
	global_load_dword v12, v2, s[8:9]
	s_add_u32 s8, s8, 0x1000
	s_addc_u32 s9, s9, 0
	global_load_dword v13, v2, s[8:9]
	s_add_u32 s8, s8, 0x1000
	s_addc_u32 s9, s9, 0
	global_load_dword v14, v2, s[8:9]
	s_add_u32 s8, s8, 0x1000
	s_addc_u32 s9, s9, 0
	global_load_dword v15, v2, s[8:9]
	s_add_u32 s8, s8, 0x1000
	s_addc_u32 s9, s9, 0
	global_load_dword v16, v2, s[8:9]
	s_add_u32 s8, s8, 0x1000
	s_addc_u32 s9, s9, 0
	global_load_dword v17, v2, s[8:9]
	s_add_u32 s8, s8, 0x1000
	s_addc_u32 s9, s9, 0
	global_load_dword v18, v2, s[8:9]
	s_add_u32 s8, s8, 0x1000
	s_addc_u32 s9, s9, 0
	global_load_dword v19, v2, s[8:9]
	s_add_u32 s8, s8, 0x1000
	s_addc_u32 s9, s9, 0
	global_load_dwordx4 v[20:23], v4, s[10:11] offset:192
	global_load_dwordx4 v[24:27], v4, s[10:11] offset:208
	global_load_dwordx4 v[28:31], v4, s[12:13] offset:192
	global_load_dwordx4 v[32:35], v4, s[12:13] offset:208
	global_load_dwordx4 v[54:57], v4, s[14:15] offset:192
	global_load_dwordx4 v[58:61], v4, s[14:15] offset:208
	global_load_dwordx4 v[62:65], v4, s[16:17] offset:192
	global_load_dwordx4 v[66:69], v4, s[16:17] offset:208
	global_load_dwordx4 v[70:73], v4, s[20:21] offset:192
	global_load_dwordx4 v[74:77], v4, s[20:21] offset:208
	s_waitcnt vmcnt(18)
; __device__ __forceinline__ void p0_prologue(const Params& p, LAS unsigned char* lds, const int wave_s) {
;     ...
;         for (int e = 0; e < 128; ++e) {
;             a0 += wp[e] * ps[e] * wo[(size_t)e * 1024];
;             a1 += wp[16384 + e] * ps[128 + e] * wo[(size_t)(128 + e) * 1024];
;             a2 += wp[32768 + e] * ps[256 + e] * wo[(size_t)(256 + e) * 1024];
;             a3 += wp[49152 + e] * ps[384 + e] * wo[(size_t)(384 + e) * 1024];
;         }
	v_mul_f32_e32 v9, v86, v118
	v_fmac_f32_e32 v5, v9, v78
	v_mul_f32_e32 v9, v94, v118
	v_fmac_f32_e32 v6, v9, v78
	v_mul_f32_e32 v9, v102, v118
	v_fmac_f32_e32 v7, v9, v78
	v_mul_f32_e32 v9, v110, v118
	v_fmac_f32_e32 v8, v9, v78
	v_mul_f32_e32 v9, v87, v119
	v_fmac_f32_e32 v5, v9, v79
	v_mul_f32_e32 v9, v95, v119
	v_fmac_f32_e32 v6, v9, v79
	v_mul_f32_e32 v9, v103, v119
	v_fmac_f32_e32 v7, v9, v79
	v_mul_f32_e32 v9, v111, v119
	v_fmac_f32_e32 v8, v9, v79
	v_mul_f32_e32 v9, v88, v120
	v_fmac_f32_e32 v5, v9, v80
	v_mul_f32_e32 v9, v96, v120
	v_fmac_f32_e32 v6, v9, v80
	v_mul_f32_e32 v9, v104, v120
	v_fmac_f32_e32 v7, v9, v80
	v_mul_f32_e32 v9, v112, v120
	v_fmac_f32_e32 v8, v9, v80
	v_mul_f32_e32 v9, v89, v121
	v_fmac_f32_e32 v5, v9, v81
	v_mul_f32_e32 v9, v97, v121
	v_fmac_f32_e32 v6, v9, v81
	v_mul_f32_e32 v9, v105, v121
	v_fmac_f32_e32 v7, v9, v81
	v_mul_f32_e32 v9, v113, v121
	v_fmac_f32_e32 v8, v9, v81
	v_mul_f32_e32 v9, v90, v122
	v_fmac_f32_e32 v5, v9, v82
	v_mul_f32_e32 v9, v98, v122
	v_fmac_f32_e32 v6, v9, v82
	v_mul_f32_e32 v9, v106, v122
	v_fmac_f32_e32 v7, v9, v82
	v_mul_f32_e32 v9, v114, v122
	v_fmac_f32_e32 v8, v9, v82
	v_mul_f32_e32 v9, v91, v123
	v_fmac_f32_e32 v5, v9, v83
	v_mul_f32_e32 v9, v99, v123
	v_fmac_f32_e32 v6, v9, v83
	v_mul_f32_e32 v9, v107, v123
	v_fmac_f32_e32 v7, v9, v83
	v_mul_f32_e32 v9, v115, v123
	v_fmac_f32_e32 v8, v9, v83
	v_mul_f32_e32 v9, v92, v124
	v_fmac_f32_e32 v5, v9, v84
	v_mul_f32_e32 v9, v100, v124
	v_fmac_f32_e32 v6, v9, v84
	v_mul_f32_e32 v9, v108, v124
	v_fmac_f32_e32 v7, v9, v84
	v_mul_f32_e32 v9, v116, v124
	v_fmac_f32_e32 v8, v9, v84
	v_mul_f32_e32 v9, v93, v125
	v_fmac_f32_e32 v5, v9, v85
	v_mul_f32_e32 v9, v101, v125
	v_fmac_f32_e32 v6, v9, v85
	v_mul_f32_e32 v9, v109, v125
	v_fmac_f32_e32 v7, v9, v85
	v_mul_f32_e32 v9, v117, v125
	v_fmac_f32_e32 v8, v9, v85
	global_load_dword v78, v2, s[8:9]
	s_add_u32 s8, s8, 0x1000
	s_addc_u32 s9, s9, 0
	global_load_dword v79, v2, s[8:9]
	s_add_u32 s8, s8, 0x1000
	s_addc_u32 s9, s9, 0
	global_load_dword v80, v2, s[8:9]
	s_add_u32 s8, s8, 0x1000
	s_addc_u32 s9, s9, 0
	global_load_dword v81, v2, s[8:9]
	s_add_u32 s8, s8, 0x1000
	s_addc_u32 s9, s9, 0
	global_load_dword v82, v2, s[8:9]
	s_add_u32 s8, s8, 0x1000
	s_addc_u32 s9, s9, 0
	global_load_dword v83, v2, s[8:9]
	s_add_u32 s8, s8, 0x1000
	s_addc_u32 s9, s9, 0
	global_load_dword v84, v2, s[8:9]
	s_add_u32 s8, s8, 0x1000
	s_addc_u32 s9, s9, 0
	global_load_dword v85, v2, s[8:9]
	s_add_u32 s8, s8, 0x1000
	s_addc_u32 s9, s9, 0
	global_load_dwordx4 v[86:89], v4, s[10:11] offset:224
	global_load_dwordx4 v[90:93], v4, s[10:11] offset:240
	global_load_dwordx4 v[94:97], v4, s[12:13] offset:224
	global_load_dwordx4 v[98:101], v4, s[12:13] offset:240
	global_load_dwordx4 v[102:105], v4, s[14:15] offset:224
	global_load_dwordx4 v[106:109], v4, s[14:15] offset:240
	global_load_dwordx4 v[110:113], v4, s[16:17] offset:224
	global_load_dwordx4 v[114:117], v4, s[16:17] offset:240
	global_load_dwordx4 v[118:121], v4, s[20:21] offset:224
	global_load_dwordx4 v[122:125], v4, s[20:21] offset:240
	s_waitcnt vmcnt(18)
	v_mul_f32_e32 v9, v20, v70
	v_fmac_f32_e32 v5, v9, v12
	v_mul_f32_e32 v9, v28, v70
	v_fmac_f32_e32 v6, v9, v12
	v_mul_f32_e32 v9, v54, v70
	v_fmac_f32_e32 v7, v9, v12
	v_mul_f32_e32 v9, v62, v70
	v_fmac_f32_e32 v8, v9, v12
	v_mul_f32_e32 v9, v21, v71
	v_fmac_f32_e32 v5, v9, v13
	v_mul_f32_e32 v9, v29, v71
	v_fmac_f32_e32 v6, v9, v13
	v_mul_f32_e32 v9, v55, v71
	v_fmac_f32_e32 v7, v9, v13
	v_mul_f32_e32 v9, v63, v71
	v_fmac_f32_e32 v8, v9, v13
	v_mul_f32_e32 v9, v22, v72
	v_fmac_f32_e32 v5, v9, v14
	v_mul_f32_e32 v9, v30, v72
	v_fmac_f32_e32 v6, v9, v14
	v_mul_f32_e32 v9, v56, v72
	v_fmac_f32_e32 v7, v9, v14
	v_mul_f32_e32 v9, v64, v72
	v_fmac_f32_e32 v8, v9, v14
	v_mul_f32_e32 v9, v23, v73
	v_fmac_f32_e32 v5, v9, v15
	v_mul_f32_e32 v9, v31, v73
	v_fmac_f32_e32 v6, v9, v15
	v_mul_f32_e32 v9, v57, v73
	v_fmac_f32_e32 v7, v9, v15
	v_mul_f32_e32 v9, v65, v73
	v_fmac_f32_e32 v8, v9, v15
	v_mul_f32_e32 v9, v24, v74
	v_fmac_f32_e32 v5, v9, v16
	v_mul_f32_e32 v9, v32, v74
	v_fmac_f32_e32 v6, v9, v16
	v_mul_f32_e32 v9, v58, v74
	v_fmac_f32_e32 v7, v9, v16
	v_mul_f32_e32 v9, v66, v74
	v_fmac_f32_e32 v8, v9, v16
	v_mul_f32_e32 v9, v25, v75
	v_fmac_f32_e32 v5, v9, v17
	v_mul_f32_e32 v9, v33, v75
	v_fmac_f32_e32 v6, v9, v17
	v_mul_f32_e32 v9, v59, v75
	v_fmac_f32_e32 v7, v9, v17
	v_mul_f32_e32 v9, v67, v75
	v_fmac_f32_e32 v8, v9, v17
	v_mul_f32_e32 v9, v26, v76
	v_fmac_f32_e32 v5, v9, v18
	v_mul_f32_e32 v9, v34, v76
	v_fmac_f32_e32 v6, v9, v18
	v_mul_f32_e32 v9, v60, v76
	v_fmac_f32_e32 v7, v9, v18
	v_mul_f32_e32 v9, v68, v76
	v_fmac_f32_e32 v8, v9, v18
	v_mul_f32_e32 v9, v27, v77
	v_fmac_f32_e32 v5, v9, v19
	v_mul_f32_e32 v9, v35, v77
	v_fmac_f32_e32 v6, v9, v19
	v_mul_f32_e32 v9, v61, v77
	v_fmac_f32_e32 v7, v9, v19
	v_mul_f32_e32 v9, v69, v77
	v_fmac_f32_e32 v8, v9, v19
	global_load_dword v12, v2, s[8:9]
	s_add_u32 s8, s8, 0x1000
	s_addc_u32 s9, s9, 0
	global_load_dword v13, v2, s[8:9]
	s_add_u32 s8, s8, 0x1000
	s_addc_u32 s9, s9, 0
	global_load_dword v14, v2, s[8:9]
	s_add_u32 s8, s8, 0x1000
	s_addc_u32 s9, s9, 0
	global_load_dword v15, v2, s[8:9]
	s_add_u32 s8, s8, 0x1000
	s_addc_u32 s9, s9, 0
	global_load_dword v16, v2, s[8:9]
	s_add_u32 s8, s8, 0x1000
	s_addc_u32 s9, s9, 0
	global_load_dword v17, v2, s[8:9]
	s_add_u32 s8, s8, 0x1000
	s_addc_u32 s9, s9, 0
	global_load_dword v18, v2, s[8:9]
	s_add_u32 s8, s8, 0x1000
	s_addc_u32 s9, s9, 0
	global_load_dword v19, v2, s[8:9]
	s_add_u32 s8, s8, 0x1000
	s_addc_u32 s9, s9, 0
	global_load_dwordx4 v[20:23], v4, s[10:11] offset:256
	global_load_dwordx4 v[24:27], v4, s[10:11] offset:272
	global_load_dwordx4 v[28:31], v4, s[12:13] offset:256
	global_load_dwordx4 v[32:35], v4, s[12:13] offset:272
	global_load_dwordx4 v[54:57], v4, s[14:15] offset:256
	global_load_dwordx4 v[58:61], v4, s[14:15] offset:272
	global_load_dwordx4 v[62:65], v4, s[16:17] offset:256
	global_load_dwordx4 v[66:69], v4, s[16:17] offset:272
	global_load_dwordx4 v[70:73], v4, s[20:21] offset:256
	global_load_dwordx4 v[74:77], v4, s[20:21] offset:272
	s_waitcnt vmcnt(18)
; __device__ __forceinline__ void p0_prologue(const Params& p, LAS unsigned char* lds, const int wave_s) {
;     ...
;         for (int e = 0; e < 128; ++e) {
;             a0 += wp[e] * ps[e] * wo[(size_t)e * 1024];
;             a1 += wp[16384 + e] * ps[128 + e] * wo[(size_t)(128 + e) * 1024];
;             a2 += wp[32768 + e] * ps[256 + e] * wo[(size_t)(256 + e) * 1024];
;             a3 += wp[49152 + e] * ps[384 + e] * wo[(size_t)(384 + e) * 1024];
;         }
	v_mul_f32_e32 v9, v86, v118
	v_fmac_f32_e32 v5, v9, v78
	v_mul_f32_e32 v9, v94, v118
	v_fmac_f32_e32 v6, v9, v78
	v_mul_f32_e32 v9, v102, v118
	v_fmac_f32_e32 v7, v9, v78
	v_mul_f32_e32 v9, v110, v118
	v_fmac_f32_e32 v8, v9, v78
	v_mul_f32_e32 v9, v87, v119
	v_fmac_f32_e32 v5, v9, v79
	v_mul_f32_e32 v9, v95, v119
	v_fmac_f32_e32 v6, v9, v79
	v_mul_f32_e32 v9, v103, v119
	v_fmac_f32_e32 v7, v9, v79
	v_mul_f32_e32 v9, v111, v119
	v_fmac_f32_e32 v8, v9, v79
	v_mul_f32_e32 v9, v88, v120
	v_fmac_f32_e32 v5, v9, v80
	v_mul_f32_e32 v9, v96, v120
	v_fmac_f32_e32 v6, v9, v80
	v_mul_f32_e32 v9, v104, v120
	v_fmac_f32_e32 v7, v9, v80
	v_mul_f32_e32 v9, v112, v120
	v_fmac_f32_e32 v8, v9, v80
	v_mul_f32_e32 v9, v89, v121
	v_fmac_f32_e32 v5, v9, v81
	v_mul_f32_e32 v9, v97, v121
	v_fmac_f32_e32 v6, v9, v81
	v_mul_f32_e32 v9, v105, v121
	v_fmac_f32_e32 v7, v9, v81
	v_mul_f32_e32 v9, v113, v121
	v_fmac_f32_e32 v8, v9, v81
	v_mul_f32_e32 v9, v90, v122
	v_fmac_f32_e32 v5, v9, v82
	v_mul_f32_e32 v9, v98, v122
	v_fmac_f32_e32 v6, v9, v82
	v_mul_f32_e32 v9, v106, v122
	v_fmac_f32_e32 v7, v9, v82
	v_mul_f32_e32 v9, v114, v122
	v_fmac_f32_e32 v8, v9, v82
	v_mul_f32_e32 v9, v91, v123
	v_fmac_f32_e32 v5, v9, v83
	v_mul_f32_e32 v9, v99, v123
	v_fmac_f32_e32 v6, v9, v83
	v_mul_f32_e32 v9, v107, v123
	v_fmac_f32_e32 v7, v9, v83
	v_mul_f32_e32 v9, v115, v123
	v_fmac_f32_e32 v8, v9, v83
	v_mul_f32_e32 v9, v92, v124
	v_fmac_f32_e32 v5, v9, v84
	v_mul_f32_e32 v9, v100, v124
	v_fmac_f32_e32 v6, v9, v84
	v_mul_f32_e32 v9, v108, v124
	v_fmac_f32_e32 v7, v9, v84
	v_mul_f32_e32 v9, v116, v124
	v_fmac_f32_e32 v8, v9, v84
	v_mul_f32_e32 v9, v93, v125
	v_fmac_f32_e32 v5, v9, v85
	v_mul_f32_e32 v9, v101, v125
	v_fmac_f32_e32 v6, v9, v85
	v_mul_f32_e32 v9, v109, v125
	v_fmac_f32_e32 v7, v9, v85
	v_mul_f32_e32 v9, v117, v125
	v_fmac_f32_e32 v8, v9, v85
	global_load_dword v78, v2, s[8:9]
	s_add_u32 s8, s8, 0x1000
	s_addc_u32 s9, s9, 0
	global_load_dword v79, v2, s[8:9]
	s_add_u32 s8, s8, 0x1000
	s_addc_u32 s9, s9, 0
	global_load_dword v80, v2, s[8:9]
	s_add_u32 s8, s8, 0x1000
	s_addc_u32 s9, s9, 0
	global_load_dword v81, v2, s[8:9]
	s_add_u32 s8, s8, 0x1000
	s_addc_u32 s9, s9, 0
	global_load_dword v82, v2, s[8:9]
	s_add_u32 s8, s8, 0x1000
	s_addc_u32 s9, s9, 0
	global_load_dword v83, v2, s[8:9]
	s_add_u32 s8, s8, 0x1000
	s_addc_u32 s9, s9, 0
	global_load_dword v84, v2, s[8:9]
	s_add_u32 s8, s8, 0x1000
	s_addc_u32 s9, s9, 0
	global_load_dword v85, v2, s[8:9]
	s_add_u32 s8, s8, 0x1000
	s_addc_u32 s9, s9, 0
	global_load_dwordx4 v[86:89], v4, s[10:11] offset:288
	global_load_dwordx4 v[90:93], v4, s[10:11] offset:304
	global_load_dwordx4 v[94:97], v4, s[12:13] offset:288
	global_load_dwordx4 v[98:101], v4, s[12:13] offset:304
	global_load_dwordx4 v[102:105], v4, s[14:15] offset:288
	global_load_dwordx4 v[106:109], v4, s[14:15] offset:304
	global_load_dwordx4 v[110:113], v4, s[16:17] offset:288
	global_load_dwordx4 v[114:117], v4, s[16:17] offset:304
	global_load_dwordx4 v[118:121], v4, s[20:21] offset:288
	global_load_dwordx4 v[122:125], v4, s[20:21] offset:304
	s_waitcnt vmcnt(18)
	v_mul_f32_e32 v9, v20, v70
	v_fmac_f32_e32 v5, v9, v12
	v_mul_f32_e32 v9, v28, v70
	v_fmac_f32_e32 v6, v9, v12
	v_mul_f32_e32 v9, v54, v70
	v_fmac_f32_e32 v7, v9, v12
	v_mul_f32_e32 v9, v62, v70
	v_fmac_f32_e32 v8, v9, v12
	v_mul_f32_e32 v9, v21, v71
	v_fmac_f32_e32 v5, v9, v13
	v_mul_f32_e32 v9, v29, v71
	v_fmac_f32_e32 v6, v9, v13
	v_mul_f32_e32 v9, v55, v71
	v_fmac_f32_e32 v7, v9, v13
	v_mul_f32_e32 v9, v63, v71
	v_fmac_f32_e32 v8, v9, v13
	v_mul_f32_e32 v9, v22, v72
	v_fmac_f32_e32 v5, v9, v14
	v_mul_f32_e32 v9, v30, v72
	v_fmac_f32_e32 v6, v9, v14
	v_mul_f32_e32 v9, v56, v72
	v_fmac_f32_e32 v7, v9, v14
	v_mul_f32_e32 v9, v64, v72
	v_fmac_f32_e32 v8, v9, v14
	v_mul_f32_e32 v9, v23, v73
	v_fmac_f32_e32 v5, v9, v15
	v_mul_f32_e32 v9, v31, v73
	v_fmac_f32_e32 v6, v9, v15
	v_mul_f32_e32 v9, v57, v73
	v_fmac_f32_e32 v7, v9, v15
	v_mul_f32_e32 v9, v65, v73
	v_fmac_f32_e32 v8, v9, v15
	v_mul_f32_e32 v9, v24, v74
	v_fmac_f32_e32 v5, v9, v16
	v_mul_f32_e32 v9, v32, v74
	v_fmac_f32_e32 v6, v9, v16
	v_mul_f32_e32 v9, v58, v74
	v_fmac_f32_e32 v7, v9, v16
	v_mul_f32_e32 v9, v66, v74
	v_fmac_f32_e32 v8, v9, v16
	v_mul_f32_e32 v9, v25, v75
	v_fmac_f32_e32 v5, v9, v17
	v_mul_f32_e32 v9, v33, v75
	v_fmac_f32_e32 v6, v9, v17
	v_mul_f32_e32 v9, v59, v75
	v_fmac_f32_e32 v7, v9, v17
	v_mul_f32_e32 v9, v67, v75
	v_fmac_f32_e32 v8, v9, v17
	v_mul_f32_e32 v9, v26, v76
	v_fmac_f32_e32 v5, v9, v18
	v_mul_f32_e32 v9, v34, v76
	v_fmac_f32_e32 v6, v9, v18
	v_mul_f32_e32 v9, v60, v76
	v_fmac_f32_e32 v7, v9, v18
	v_mul_f32_e32 v9, v68, v76
	v_fmac_f32_e32 v8, v9, v18
	v_mul_f32_e32 v9, v27, v77
	v_fmac_f32_e32 v5, v9, v19
	v_mul_f32_e32 v9, v35, v77
	v_fmac_f32_e32 v6, v9, v19
	v_mul_f32_e32 v9, v61, v77
	v_fmac_f32_e32 v7, v9, v19
	v_mul_f32_e32 v9, v69, v77
	v_fmac_f32_e32 v8, v9, v19
	global_load_dword v12, v2, s[8:9]
	s_add_u32 s8, s8, 0x1000
	s_addc_u32 s9, s9, 0
	global_load_dword v13, v2, s[8:9]
	s_add_u32 s8, s8, 0x1000
	s_addc_u32 s9, s9, 0
	global_load_dword v14, v2, s[8:9]
	s_add_u32 s8, s8, 0x1000
	s_addc_u32 s9, s9, 0
	global_load_dword v15, v2, s[8:9]
	s_add_u32 s8, s8, 0x1000
	s_addc_u32 s9, s9, 0
	global_load_dword v16, v2, s[8:9]
	s_add_u32 s8, s8, 0x1000
	s_addc_u32 s9, s9, 0
	global_load_dword v17, v2, s[8:9]
	s_add_u32 s8, s8, 0x1000
	s_addc_u32 s9, s9, 0
	global_load_dword v18, v2, s[8:9]
	s_add_u32 s8, s8, 0x1000
	s_addc_u32 s9, s9, 0
	global_load_dword v19, v2, s[8:9]
	s_add_u32 s8, s8, 0x1000
	s_addc_u32 s9, s9, 0
	global_load_dwordx4 v[20:23], v4, s[10:11] offset:320
	global_load_dwordx4 v[24:27], v4, s[10:11] offset:336
	global_load_dwordx4 v[28:31], v4, s[12:13] offset:320
	global_load_dwordx4 v[32:35], v4, s[12:13] offset:336
	global_load_dwordx4 v[54:57], v4, s[14:15] offset:320
	global_load_dwordx4 v[58:61], v4, s[14:15] offset:336
	global_load_dwordx4 v[62:65], v4, s[16:17] offset:320
	global_load_dwordx4 v[66:69], v4, s[16:17] offset:336
	global_load_dwordx4 v[70:73], v4, s[20:21] offset:320
	global_load_dwordx4 v[74:77], v4, s[20:21] offset:336
	s_waitcnt vmcnt(18)
; __device__ __forceinline__ void p0_prologue(const Params& p, LAS unsigned char* lds, const int wave_s) {
;     ...
;         for (int e = 0; e < 128; ++e) {
;             a0 += wp[e] * ps[e] * wo[(size_t)e * 1024];
;             a1 += wp[16384 + e] * ps[128 + e] * wo[(size_t)(128 + e) * 1024];
;             a2 += wp[32768 + e] * ps[256 + e] * wo[(size_t)(256 + e) * 1024];
;             a3 += wp[49152 + e] * ps[384 + e] * wo[(size_t)(384 + e) * 1024];
;         }
	v_mul_f32_e32 v9, v86, v118
	v_fmac_f32_e32 v5, v9, v78
	v_mul_f32_e32 v9, v94, v118
	v_fmac_f32_e32 v6, v9, v78
	v_mul_f32_e32 v9, v102, v118
	v_fmac_f32_e32 v7, v9, v78
	v_mul_f32_e32 v9, v110, v118
	v_fmac_f32_e32 v8, v9, v78
	v_mul_f32_e32 v9, v87, v119
	v_fmac_f32_e32 v5, v9, v79
	v_mul_f32_e32 v9, v95, v119
	v_fmac_f32_e32 v6, v9, v79
	v_mul_f32_e32 v9, v103, v119
	v_fmac_f32_e32 v7, v9, v79
	v_mul_f32_e32 v9, v111, v119
	v_fmac_f32_e32 v8, v9, v79
	v_mul_f32_e32 v9, v88, v120
	v_fmac_f32_e32 v5, v9, v80
	v_mul_f32_e32 v9, v96, v120
	v_fmac_f32_e32 v6, v9, v80
	v_mul_f32_e32 v9, v104, v120
	v_fmac_f32_e32 v7, v9, v80
	v_mul_f32_e32 v9, v112, v120
	v_fmac_f32_e32 v8, v9, v80
	v_mul_f32_e32 v9, v89, v121
	v_fmac_f32_e32 v5, v9, v81
	v_mul_f32_e32 v9, v97, v121
	v_fmac_f32_e32 v6, v9, v81
	v_mul_f32_e32 v9, v105, v121
	v_fmac_f32_e32 v7, v9, v81
	v_mul_f32_e32 v9, v113, v121
	v_fmac_f32_e32 v8, v9, v81
	v_mul_f32_e32 v9, v90, v122
	v_fmac_f32_e32 v5, v9, v82
	v_mul_f32_e32 v9, v98, v122
	v_fmac_f32_e32 v6, v9, v82
	v_mul_f32_e32 v9, v106, v122
	v_fmac_f32_e32 v7, v9, v82
	v_mul_f32_e32 v9, v114, v122
	v_fmac_f32_e32 v8, v9, v82
	v_mul_f32_e32 v9, v91, v123
	v_fmac_f32_e32 v5, v9, v83
	v_mul_f32_e32 v9, v99, v123
	v_fmac_f32_e32 v6, v9, v83
	v_mul_f32_e32 v9, v107, v123
	v_fmac_f32_e32 v7, v9, v83
	v_mul_f32_e32 v9, v115, v123
	v_fmac_f32_e32 v8, v9, v83
	v_mul_f32_e32 v9, v92, v124
	v_fmac_f32_e32 v5, v9, v84
	v_mul_f32_e32 v9, v100, v124
	v_fmac_f32_e32 v6, v9, v84
	v_mul_f32_e32 v9, v108, v124
	v_fmac_f32_e32 v7, v9, v84
	v_mul_f32_e32 v9, v116, v124
	v_fmac_f32_e32 v8, v9, v84
	v_mul_f32_e32 v9, v93, v125
	v_fmac_f32_e32 v5, v9, v85
	v_mul_f32_e32 v9, v101, v125
	v_fmac_f32_e32 v6, v9, v85
	v_mul_f32_e32 v9, v109, v125
	v_fmac_f32_e32 v7, v9, v85
	v_mul_f32_e32 v9, v117, v125
	v_fmac_f32_e32 v8, v9, v85
	global_load_dword v78, v2, s[8:9]
	s_add_u32 s8, s8, 0x1000
	s_addc_u32 s9, s9, 0
	global_load_dword v79, v2, s[8:9]
	s_add_u32 s8, s8, 0x1000
	s_addc_u32 s9, s9, 0
	global_load_dword v80, v2, s[8:9]
	s_add_u32 s8, s8, 0x1000
	s_addc_u32 s9, s9, 0
	global_load_dword v81, v2, s[8:9]
	s_add_u32 s8, s8, 0x1000
	s_addc_u32 s9, s9, 0
	global_load_dword v82, v2, s[8:9]
	s_add_u32 s8, s8, 0x1000
	s_addc_u32 s9, s9, 0
	global_load_dword v83, v2, s[8:9]
	s_add_u32 s8, s8, 0x1000
	s_addc_u32 s9, s9, 0
	global_load_dword v84, v2, s[8:9]
	s_add_u32 s8, s8, 0x1000
	s_addc_u32 s9, s9, 0
	global_load_dword v85, v2, s[8:9]
	s_add_u32 s8, s8, 0x1000
	s_addc_u32 s9, s9, 0
	global_load_dwordx4 v[86:89], v4, s[10:11] offset:352
	global_load_dwordx4 v[90:93], v4, s[10:11] offset:368
	global_load_dwordx4 v[94:97], v4, s[12:13] offset:352
	global_load_dwordx4 v[98:101], v4, s[12:13] offset:368
	global_load_dwordx4 v[102:105], v4, s[14:15] offset:352
	global_load_dwordx4 v[106:109], v4, s[14:15] offset:368
	global_load_dwordx4 v[110:113], v4, s[16:17] offset:352
	global_load_dwordx4 v[114:117], v4, s[16:17] offset:368
	global_load_dwordx4 v[118:121], v4, s[20:21] offset:352
	global_load_dwordx4 v[122:125], v4, s[20:21] offset:368
	s_waitcnt vmcnt(18)
	v_mul_f32_e32 v9, v20, v70
	v_fmac_f32_e32 v5, v9, v12
	v_mul_f32_e32 v9, v28, v70
	v_fmac_f32_e32 v6, v9, v12
	v_mul_f32_e32 v9, v54, v70
	v_fmac_f32_e32 v7, v9, v12
	v_mul_f32_e32 v9, v62, v70
	v_fmac_f32_e32 v8, v9, v12
	v_mul_f32_e32 v9, v21, v71
	v_fmac_f32_e32 v5, v9, v13
	v_mul_f32_e32 v9, v29, v71
	v_fmac_f32_e32 v6, v9, v13
	v_mul_f32_e32 v9, v55, v71
	v_fmac_f32_e32 v7, v9, v13
	v_mul_f32_e32 v9, v63, v71
	v_fmac_f32_e32 v8, v9, v13
	v_mul_f32_e32 v9, v22, v72
	v_fmac_f32_e32 v5, v9, v14
	v_mul_f32_e32 v9, v30, v72
	v_fmac_f32_e32 v6, v9, v14
	v_mul_f32_e32 v9, v56, v72
	v_fmac_f32_e32 v7, v9, v14
	v_mul_f32_e32 v9, v64, v72
	v_fmac_f32_e32 v8, v9, v14
	v_mul_f32_e32 v9, v23, v73
	v_fmac_f32_e32 v5, v9, v15
	v_mul_f32_e32 v9, v31, v73
	v_fmac_f32_e32 v6, v9, v15
	v_mul_f32_e32 v9, v57, v73
	v_fmac_f32_e32 v7, v9, v15
	v_mul_f32_e32 v9, v65, v73
	v_fmac_f32_e32 v8, v9, v15
	v_mul_f32_e32 v9, v24, v74
	v_fmac_f32_e32 v5, v9, v16
	v_mul_f32_e32 v9, v32, v74
	v_fmac_f32_e32 v6, v9, v16
	v_mul_f32_e32 v9, v58, v74
	v_fmac_f32_e32 v7, v9, v16
	v_mul_f32_e32 v9, v66, v74
	v_fmac_f32_e32 v8, v9, v16
	v_mul_f32_e32 v9, v25, v75
	v_fmac_f32_e32 v5, v9, v17
	v_mul_f32_e32 v9, v33, v75
	v_fmac_f32_e32 v6, v9, v17
	v_mul_f32_e32 v9, v59, v75
	v_fmac_f32_e32 v7, v9, v17
	v_mul_f32_e32 v9, v67, v75
	v_fmac_f32_e32 v8, v9, v17
	v_mul_f32_e32 v9, v26, v76
	v_fmac_f32_e32 v5, v9, v18
	v_mul_f32_e32 v9, v34, v76
	v_fmac_f32_e32 v6, v9, v18
	v_mul_f32_e32 v9, v60, v76
	v_fmac_f32_e32 v7, v9, v18
	v_mul_f32_e32 v9, v68, v76
	v_fmac_f32_e32 v8, v9, v18
	v_mul_f32_e32 v9, v27, v77
	v_fmac_f32_e32 v5, v9, v19
	v_mul_f32_e32 v9, v35, v77
	v_fmac_f32_e32 v6, v9, v19
	v_mul_f32_e32 v9, v61, v77
	v_fmac_f32_e32 v7, v9, v19
	v_mul_f32_e32 v9, v69, v77
	v_fmac_f32_e32 v8, v9, v19
	global_load_dword v12, v2, s[8:9]
	s_add_u32 s8, s8, 0x1000
	s_addc_u32 s9, s9, 0
	global_load_dword v13, v2, s[8:9]
	s_add_u32 s8, s8, 0x1000
	s_addc_u32 s9, s9, 0
	global_load_dword v14, v2, s[8:9]
	s_add_u32 s8, s8, 0x1000
	s_addc_u32 s9, s9, 0
	global_load_dword v15, v2, s[8:9]
	s_add_u32 s8, s8, 0x1000
	s_addc_u32 s9, s9, 0
	global_load_dword v16, v2, s[8:9]
	s_add_u32 s8, s8, 0x1000
	s_addc_u32 s9, s9, 0
	global_load_dword v17, v2, s[8:9]
	s_add_u32 s8, s8, 0x1000
	s_addc_u32 s9, s9, 0
	global_load_dword v18, v2, s[8:9]
	s_add_u32 s8, s8, 0x1000
	s_addc_u32 s9, s9, 0
	global_load_dword v19, v2, s[8:9]
	s_add_u32 s8, s8, 0x1000
	s_addc_u32 s9, s9, 0
	global_load_dwordx4 v[20:23], v4, s[10:11] offset:384
	global_load_dwordx4 v[24:27], v4, s[10:11] offset:400
	global_load_dwordx4 v[28:31], v4, s[12:13] offset:384
	global_load_dwordx4 v[32:35], v4, s[12:13] offset:400
	global_load_dwordx4 v[54:57], v4, s[14:15] offset:384
	global_load_dwordx4 v[58:61], v4, s[14:15] offset:400
	global_load_dwordx4 v[62:65], v4, s[16:17] offset:384
	global_load_dwordx4 v[66:69], v4, s[16:17] offset:400
	global_load_dwordx4 v[70:73], v4, s[20:21] offset:384
	global_load_dwordx4 v[74:77], v4, s[20:21] offset:400
	s_waitcnt vmcnt(18)
; __device__ __forceinline__ void p0_prologue(const Params& p, LAS unsigned char* lds, const int wave_s) {
;     ...
;         for (int e = 0; e < 128; ++e) {
;             a0 += wp[e] * ps[e] * wo[(size_t)e * 1024];
;             a1 += wp[16384 + e] * ps[128 + e] * wo[(size_t)(128 + e) * 1024];
;             a2 += wp[32768 + e] * ps[256 + e] * wo[(size_t)(256 + e) * 1024];
;             a3 += wp[49152 + e] * ps[384 + e] * wo[(size_t)(384 + e) * 1024];
;         }
	v_mul_f32_e32 v9, v86, v118
	v_fmac_f32_e32 v5, v9, v78
	v_mul_f32_e32 v9, v94, v118
	v_fmac_f32_e32 v6, v9, v78
	v_mul_f32_e32 v9, v102, v118
	v_fmac_f32_e32 v7, v9, v78
	v_mul_f32_e32 v9, v110, v118
	v_fmac_f32_e32 v8, v9, v78
	v_mul_f32_e32 v9, v87, v119
	v_fmac_f32_e32 v5, v9, v79
	v_mul_f32_e32 v9, v95, v119
	v_fmac_f32_e32 v6, v9, v79
	v_mul_f32_e32 v9, v103, v119
	v_fmac_f32_e32 v7, v9, v79
	v_mul_f32_e32 v9, v111, v119
	v_fmac_f32_e32 v8, v9, v79
	v_mul_f32_e32 v9, v88, v120
	v_fmac_f32_e32 v5, v9, v80
	v_mul_f32_e32 v9, v96, v120
	v_fmac_f32_e32 v6, v9, v80
	v_mul_f32_e32 v9, v104, v120
	v_fmac_f32_e32 v7, v9, v80
	v_mul_f32_e32 v9, v112, v120
	v_fmac_f32_e32 v8, v9, v80
	v_mul_f32_e32 v9, v89, v121
	v_fmac_f32_e32 v5, v9, v81
	v_mul_f32_e32 v9, v97, v121
	v_fmac_f32_e32 v6, v9, v81
	v_mul_f32_e32 v9, v105, v121
	v_fmac_f32_e32 v7, v9, v81
	v_mul_f32_e32 v9, v113, v121
	v_fmac_f32_e32 v8, v9, v81
	v_mul_f32_e32 v9, v90, v122
	v_fmac_f32_e32 v5, v9, v82
	v_mul_f32_e32 v9, v98, v122
	v_fmac_f32_e32 v6, v9, v82
	v_mul_f32_e32 v9, v106, v122
	v_fmac_f32_e32 v7, v9, v82
	v_mul_f32_e32 v9, v114, v122
	v_fmac_f32_e32 v8, v9, v82
	v_mul_f32_e32 v9, v91, v123
	v_fmac_f32_e32 v5, v9, v83
	v_mul_f32_e32 v9, v99, v123
	v_fmac_f32_e32 v6, v9, v83
	v_mul_f32_e32 v9, v107, v123
	v_fmac_f32_e32 v7, v9, v83
	v_mul_f32_e32 v9, v115, v123
	v_fmac_f32_e32 v8, v9, v83
	v_mul_f32_e32 v9, v92, v124
	v_fmac_f32_e32 v5, v9, v84
	v_mul_f32_e32 v9, v100, v124
	v_fmac_f32_e32 v6, v9, v84
	v_mul_f32_e32 v9, v108, v124
	v_fmac_f32_e32 v7, v9, v84
	v_mul_f32_e32 v9, v116, v124
	v_fmac_f32_e32 v8, v9, v84
	v_mul_f32_e32 v9, v93, v125
	v_fmac_f32_e32 v5, v9, v85
	v_mul_f32_e32 v9, v101, v125
	v_fmac_f32_e32 v6, v9, v85
	v_mul_f32_e32 v9, v109, v125
	v_fmac_f32_e32 v7, v9, v85
	v_mul_f32_e32 v9, v117, v125
	v_fmac_f32_e32 v8, v9, v85
	global_load_dword v78, v2, s[8:9]
	s_add_u32 s8, s8, 0x1000
	s_addc_u32 s9, s9, 0
	global_load_dword v79, v2, s[8:9]
	s_add_u32 s8, s8, 0x1000
	s_addc_u32 s9, s9, 0
	global_load_dword v80, v2, s[8:9]
	s_add_u32 s8, s8, 0x1000
	s_addc_u32 s9, s9, 0
	global_load_dword v81, v2, s[8:9]
	s_add_u32 s8, s8, 0x1000
	s_addc_u32 s9, s9, 0
	global_load_dword v82, v2, s[8:9]
	s_add_u32 s8, s8, 0x1000
	s_addc_u32 s9, s9, 0
	global_load_dword v83, v2, s[8:9]
	s_add_u32 s8, s8, 0x1000
	s_addc_u32 s9, s9, 0
	global_load_dword v84, v2, s[8:9]
	s_add_u32 s8, s8, 0x1000
	s_addc_u32 s9, s9, 0
	global_load_dword v85, v2, s[8:9]
	s_add_u32 s8, s8, 0x1000
	s_addc_u32 s9, s9, 0
	global_load_dwordx4 v[86:89], v4, s[10:11] offset:416
	global_load_dwordx4 v[90:93], v4, s[10:11] offset:432
	global_load_dwordx4 v[94:97], v4, s[12:13] offset:416
	global_load_dwordx4 v[98:101], v4, s[12:13] offset:432
	global_load_dwordx4 v[102:105], v4, s[14:15] offset:416
	global_load_dwordx4 v[106:109], v4, s[14:15] offset:432
	global_load_dwordx4 v[110:113], v4, s[16:17] offset:416
	global_load_dwordx4 v[114:117], v4, s[16:17] offset:432
	global_load_dwordx4 v[118:121], v4, s[20:21] offset:416
	global_load_dwordx4 v[122:125], v4, s[20:21] offset:432
	s_waitcnt vmcnt(18)
	v_mul_f32_e32 v9, v20, v70
	v_fmac_f32_e32 v5, v9, v12
	v_mul_f32_e32 v9, v28, v70
	v_fmac_f32_e32 v6, v9, v12
	v_mul_f32_e32 v9, v54, v70
	v_fmac_f32_e32 v7, v9, v12
	v_mul_f32_e32 v9, v62, v70
	v_fmac_f32_e32 v8, v9, v12
	v_mul_f32_e32 v9, v21, v71
	v_fmac_f32_e32 v5, v9, v13
	v_mul_f32_e32 v9, v29, v71
	v_fmac_f32_e32 v6, v9, v13
	v_mul_f32_e32 v9, v55, v71
	v_fmac_f32_e32 v7, v9, v13
	v_mul_f32_e32 v9, v63, v71
	v_fmac_f32_e32 v8, v9, v13
	v_mul_f32_e32 v9, v22, v72
	v_fmac_f32_e32 v5, v9, v14
	v_mul_f32_e32 v9, v30, v72
	v_fmac_f32_e32 v6, v9, v14
	v_mul_f32_e32 v9, v56, v72
	v_fmac_f32_e32 v7, v9, v14
	v_mul_f32_e32 v9, v64, v72
	v_fmac_f32_e32 v8, v9, v14
	v_mul_f32_e32 v9, v23, v73
	v_fmac_f32_e32 v5, v9, v15
	v_mul_f32_e32 v9, v31, v73
	v_fmac_f32_e32 v6, v9, v15
	v_mul_f32_e32 v9, v57, v73
	v_fmac_f32_e32 v7, v9, v15
	v_mul_f32_e32 v9, v65, v73
	v_fmac_f32_e32 v8, v9, v15
	v_mul_f32_e32 v9, v24, v74
	v_fmac_f32_e32 v5, v9, v16
	v_mul_f32_e32 v9, v32, v74
	v_fmac_f32_e32 v6, v9, v16
	v_mul_f32_e32 v9, v58, v74
	v_fmac_f32_e32 v7, v9, v16
	v_mul_f32_e32 v9, v66, v74
	v_fmac_f32_e32 v8, v9, v16
	v_mul_f32_e32 v9, v25, v75
	v_fmac_f32_e32 v5, v9, v17
	v_mul_f32_e32 v9, v33, v75
	v_fmac_f32_e32 v6, v9, v17
	v_mul_f32_e32 v9, v59, v75
	v_fmac_f32_e32 v7, v9, v17
	v_mul_f32_e32 v9, v67, v75
	v_fmac_f32_e32 v8, v9, v17
	v_mul_f32_e32 v9, v26, v76
	v_fmac_f32_e32 v5, v9, v18
	v_mul_f32_e32 v9, v34, v76
	v_fmac_f32_e32 v6, v9, v18
	v_mul_f32_e32 v9, v60, v76
	v_fmac_f32_e32 v7, v9, v18
	v_mul_f32_e32 v9, v68, v76
	v_fmac_f32_e32 v8, v9, v18
	v_mul_f32_e32 v9, v27, v77
	v_fmac_f32_e32 v5, v9, v19
	v_mul_f32_e32 v9, v35, v77
	v_fmac_f32_e32 v6, v9, v19
	v_mul_f32_e32 v9, v61, v77
	v_fmac_f32_e32 v7, v9, v19
	v_mul_f32_e32 v9, v69, v77
	v_fmac_f32_e32 v8, v9, v19
	global_load_dword v12, v2, s[8:9]
	s_add_u32 s8, s8, 0x1000
	s_addc_u32 s9, s9, 0
	global_load_dword v13, v2, s[8:9]
	s_add_u32 s8, s8, 0x1000
	s_addc_u32 s9, s9, 0
	global_load_dword v14, v2, s[8:9]
	s_add_u32 s8, s8, 0x1000
	s_addc_u32 s9, s9, 0
	global_load_dword v15, v2, s[8:9]
	s_add_u32 s8, s8, 0x1000
	s_addc_u32 s9, s9, 0
	global_load_dword v16, v2, s[8:9]
	s_add_u32 s8, s8, 0x1000
	s_addc_u32 s9, s9, 0
	global_load_dword v17, v2, s[8:9]
	s_add_u32 s8, s8, 0x1000
	s_addc_u32 s9, s9, 0
	global_load_dword v18, v2, s[8:9]
	s_add_u32 s8, s8, 0x1000
	s_addc_u32 s9, s9, 0
	global_load_dword v19, v2, s[8:9]
	s_add_u32 s8, s8, 0x1000
	s_addc_u32 s9, s9, 0
	global_load_dwordx4 v[20:23], v4, s[10:11] offset:448
	global_load_dwordx4 v[24:27], v4, s[10:11] offset:464
	global_load_dwordx4 v[28:31], v4, s[12:13] offset:448
	global_load_dwordx4 v[32:35], v4, s[12:13] offset:464
	global_load_dwordx4 v[54:57], v4, s[14:15] offset:448
	global_load_dwordx4 v[58:61], v4, s[14:15] offset:464
	global_load_dwordx4 v[62:65], v4, s[16:17] offset:448
	global_load_dwordx4 v[66:69], v4, s[16:17] offset:464
	global_load_dwordx4 v[70:73], v4, s[20:21] offset:448
	global_load_dwordx4 v[74:77], v4, s[20:21] offset:464
	s_waitcnt vmcnt(18)
; __device__ __forceinline__ bf16_t f2bf(float x) { unsigned u = __float_as_uint(x); u += 0x7fffu + ((u >> 16) & 1u); return (bf16_t)(u >> 16); }
; __device__ __forceinline__ void p0_prologue(const Params& p, LAS unsigned char* lds, const int wave_s) {
;     ...
;         for (int e = 0; e < 128; ++e) {
;             a0 += wp[e] * ps[e] * wo[(size_t)e * 1024];
;             a1 += wp[16384 + e] * ps[128 + e] * wo[(size_t)(128 + e) * 1024];
;             a2 += wp[32768 + e] * ps[256 + e] * wo[(size_t)(256 + e) * 1024];
;             a3 += wp[49152 + e] * ps[384 + e] * wo[(size_t)(384 + e) * 1024];
;         }
;         bf16_t* dst = WOUT + (size_t)n * 1024 + 512 + c;
;         dst[0] = f2bf(a0); dst[128] = f2bf(a1); dst[256] = f2bf(a2); dst[384] = f2bf(a3);
	v_mul_f32_e32 v9, v86, v118
	v_fmac_f32_e32 v5, v9, v78
	v_mul_f32_e32 v9, v94, v118
	v_fmac_f32_e32 v6, v9, v78
	v_mul_f32_e32 v9, v102, v118
	v_fmac_f32_e32 v7, v9, v78
	v_mul_f32_e32 v9, v110, v118
	v_fmac_f32_e32 v8, v9, v78
	v_mul_f32_e32 v9, v87, v119
	v_fmac_f32_e32 v5, v9, v79
	v_mul_f32_e32 v9, v95, v119
	v_fmac_f32_e32 v6, v9, v79
	v_mul_f32_e32 v9, v103, v119
	v_fmac_f32_e32 v7, v9, v79
	v_mul_f32_e32 v9, v111, v119
	v_fmac_f32_e32 v8, v9, v79
	v_mul_f32_e32 v9, v88, v120
	v_fmac_f32_e32 v5, v9, v80
	v_mul_f32_e32 v9, v96, v120
	v_fmac_f32_e32 v6, v9, v80
	v_mul_f32_e32 v9, v104, v120
	v_fmac_f32_e32 v7, v9, v80
	v_mul_f32_e32 v9, v112, v120
	v_fmac_f32_e32 v8, v9, v80
	v_mul_f32_e32 v9, v89, v121
	v_fmac_f32_e32 v5, v9, v81
	v_mul_f32_e32 v9, v97, v121
	v_fmac_f32_e32 v6, v9, v81
	v_mul_f32_e32 v9, v105, v121
	v_fmac_f32_e32 v7, v9, v81
	v_mul_f32_e32 v9, v113, v121
	v_fmac_f32_e32 v8, v9, v81
	v_mul_f32_e32 v9, v90, v122
	v_fmac_f32_e32 v5, v9, v82
	v_mul_f32_e32 v9, v98, v122
	v_fmac_f32_e32 v6, v9, v82
	v_mul_f32_e32 v9, v106, v122
	v_fmac_f32_e32 v7, v9, v82
	v_mul_f32_e32 v9, v114, v122
	v_fmac_f32_e32 v8, v9, v82
	v_mul_f32_e32 v9, v91, v123
	v_fmac_f32_e32 v5, v9, v83
	v_mul_f32_e32 v9, v99, v123
	v_fmac_f32_e32 v6, v9, v83
	v_mul_f32_e32 v9, v107, v123
	v_fmac_f32_e32 v7, v9, v83
	v_mul_f32_e32 v9, v115, v123
	v_fmac_f32_e32 v8, v9, v83
	v_mul_f32_e32 v9, v92, v124
	v_fmac_f32_e32 v5, v9, v84
	v_mul_f32_e32 v9, v100, v124
	v_fmac_f32_e32 v6, v9, v84
	v_mul_f32_e32 v9, v108, v124
	v_fmac_f32_e32 v7, v9, v84
	v_mul_f32_e32 v9, v116, v124
	v_fmac_f32_e32 v8, v9, v84
	v_mul_f32_e32 v9, v93, v125
	v_fmac_f32_e32 v5, v9, v85
	v_mul_f32_e32 v9, v101, v125
	v_fmac_f32_e32 v6, v9, v85
	v_mul_f32_e32 v9, v109, v125
	v_fmac_f32_e32 v7, v9, v85
	v_mul_f32_e32 v9, v117, v125
	v_fmac_f32_e32 v8, v9, v85
	global_load_dword v78, v2, s[8:9]
	s_add_u32 s8, s8, 0x1000
	s_addc_u32 s9, s9, 0
	global_load_dword v79, v2, s[8:9]
	s_add_u32 s8, s8, 0x1000
	s_addc_u32 s9, s9, 0
	global_load_dword v80, v2, s[8:9]
	s_add_u32 s8, s8, 0x1000
	s_addc_u32 s9, s9, 0
	global_load_dword v81, v2, s[8:9]
	s_add_u32 s8, s8, 0x1000
	s_addc_u32 s9, s9, 0
	global_load_dword v82, v2, s[8:9]
	s_add_u32 s8, s8, 0x1000
	s_addc_u32 s9, s9, 0
	global_load_dword v83, v2, s[8:9]
	s_add_u32 s8, s8, 0x1000
	s_addc_u32 s9, s9, 0
	global_load_dword v84, v2, s[8:9]
	s_add_u32 s8, s8, 0x1000
	s_addc_u32 s9, s9, 0
	global_load_dword v85, v2, s[8:9]
	s_add_u32 s8, s8, 0x1000
	s_addc_u32 s9, s9, 0
	global_load_dwordx4 v[86:89], v4, s[10:11] offset:480
	global_load_dwordx4 v[90:93], v4, s[10:11] offset:496
	global_load_dwordx4 v[94:97], v4, s[12:13] offset:480
	global_load_dwordx4 v[98:101], v4, s[12:13] offset:496
	global_load_dwordx4 v[102:105], v4, s[14:15] offset:480
	global_load_dwordx4 v[106:109], v4, s[14:15] offset:496
	global_load_dwordx4 v[110:113], v4, s[16:17] offset:480
	global_load_dwordx4 v[114:117], v4, s[16:17] offset:496
	global_load_dwordx4 v[118:121], v4, s[20:21] offset:480
	global_load_dwordx4 v[122:125], v4, s[20:21] offset:496
	s_waitcnt vmcnt(18)
	v_mul_f32_e32 v9, v20, v70
	v_fmac_f32_e32 v5, v9, v12
	v_mul_f32_e32 v9, v28, v70
	v_fmac_f32_e32 v6, v9, v12
	v_mul_f32_e32 v9, v54, v70
	v_fmac_f32_e32 v7, v9, v12
	v_mul_f32_e32 v9, v62, v70
	v_fmac_f32_e32 v8, v9, v12
	v_mul_f32_e32 v9, v21, v71
	v_fmac_f32_e32 v5, v9, v13
	v_mul_f32_e32 v9, v29, v71
	v_fmac_f32_e32 v6, v9, v13
	v_mul_f32_e32 v9, v55, v71
	v_fmac_f32_e32 v7, v9, v13
	v_mul_f32_e32 v9, v63, v71
	v_fmac_f32_e32 v8, v9, v13
	v_mul_f32_e32 v9, v22, v72
	v_fmac_f32_e32 v5, v9, v14
	v_mul_f32_e32 v9, v30, v72
	v_fmac_f32_e32 v6, v9, v14
	v_mul_f32_e32 v9, v56, v72
	v_fmac_f32_e32 v7, v9, v14
	v_mul_f32_e32 v9, v64, v72
	v_fmac_f32_e32 v8, v9, v14
	v_mul_f32_e32 v9, v23, v73
	v_fmac_f32_e32 v5, v9, v15
	v_mul_f32_e32 v9, v31, v73
	v_fmac_f32_e32 v6, v9, v15
	v_mul_f32_e32 v9, v57, v73
	v_fmac_f32_e32 v7, v9, v15
	v_mul_f32_e32 v9, v65, v73
	v_fmac_f32_e32 v8, v9, v15
	v_mul_f32_e32 v9, v24, v74
	v_fmac_f32_e32 v5, v9, v16
	v_mul_f32_e32 v9, v32, v74
	v_fmac_f32_e32 v6, v9, v16
	v_mul_f32_e32 v9, v58, v74
	v_fmac_f32_e32 v7, v9, v16
	v_mul_f32_e32 v9, v66, v74
	v_fmac_f32_e32 v8, v9, v16
	v_mul_f32_e32 v9, v25, v75
	v_fmac_f32_e32 v5, v9, v17
	v_mul_f32_e32 v9, v33, v75
	v_fmac_f32_e32 v6, v9, v17
	v_mul_f32_e32 v9, v59, v75
	v_fmac_f32_e32 v7, v9, v17
	v_mul_f32_e32 v9, v67, v75
	v_fmac_f32_e32 v8, v9, v17
	v_mul_f32_e32 v9, v26, v76
	v_fmac_f32_e32 v5, v9, v18
	v_mul_f32_e32 v9, v34, v76
	v_fmac_f32_e32 v6, v9, v18
	v_mul_f32_e32 v9, v60, v76
	v_fmac_f32_e32 v7, v9, v18
	v_mul_f32_e32 v9, v68, v76
	v_fmac_f32_e32 v8, v9, v18
	v_mul_f32_e32 v9, v27, v77
	v_fmac_f32_e32 v5, v9, v19
	v_mul_f32_e32 v9, v35, v77
	v_fmac_f32_e32 v6, v9, v19
	v_mul_f32_e32 v9, v61, v77
	v_fmac_f32_e32 v7, v9, v19
	v_mul_f32_e32 v9, v69, v77
	v_fmac_f32_e32 v8, v9, v19
	s_waitcnt vmcnt(0)
	v_mul_f32_e32 v9, v86, v118
	v_fmac_f32_e32 v5, v9, v78
	v_mul_f32_e32 v9, v94, v118
	v_fmac_f32_e32 v6, v9, v78
	v_mul_f32_e32 v9, v102, v118
	v_fmac_f32_e32 v7, v9, v78
	v_mul_f32_e32 v9, v110, v118
	v_fmac_f32_e32 v8, v9, v78
	v_mul_f32_e32 v9, v87, v119
	v_fmac_f32_e32 v5, v9, v79
	v_mul_f32_e32 v9, v95, v119
	v_fmac_f32_e32 v6, v9, v79
	v_mul_f32_e32 v9, v103, v119
	v_fmac_f32_e32 v7, v9, v79
	v_mul_f32_e32 v9, v111, v119
	v_fmac_f32_e32 v8, v9, v79
	v_mul_f32_e32 v9, v88, v120
	v_fmac_f32_e32 v5, v9, v80
	v_mul_f32_e32 v9, v96, v120
	v_fmac_f32_e32 v6, v9, v80
	v_mul_f32_e32 v9, v104, v120
	v_fmac_f32_e32 v7, v9, v80
	v_mul_f32_e32 v9, v112, v120
	v_fmac_f32_e32 v8, v9, v80
	v_mul_f32_e32 v9, v89, v121
	v_fmac_f32_e32 v5, v9, v81
	v_mul_f32_e32 v9, v97, v121
	v_fmac_f32_e32 v6, v9, v81
	v_mul_f32_e32 v9, v105, v121
	v_fmac_f32_e32 v7, v9, v81
	v_mul_f32_e32 v9, v113, v121
	v_fmac_f32_e32 v8, v9, v81
	v_mul_f32_e32 v9, v90, v122
	v_fmac_f32_e32 v5, v9, v82
	v_mul_f32_e32 v9, v98, v122
	v_fmac_f32_e32 v6, v9, v82
	v_mul_f32_e32 v9, v106, v122
	v_fmac_f32_e32 v7, v9, v82
	v_mul_f32_e32 v9, v114, v122
	v_fmac_f32_e32 v8, v9, v82
	v_mul_f32_e32 v9, v91, v123
	v_fmac_f32_e32 v5, v9, v83
	v_mul_f32_e32 v9, v99, v123
	v_fmac_f32_e32 v6, v9, v83
	v_mul_f32_e32 v9, v107, v123
	v_fmac_f32_e32 v7, v9, v83
	v_mul_f32_e32 v9, v115, v123
	v_fmac_f32_e32 v8, v9, v83
	v_mul_f32_e32 v9, v92, v124
	v_fmac_f32_e32 v5, v9, v84
	v_mul_f32_e32 v9, v100, v124
	v_fmac_f32_e32 v6, v9, v84
	v_mul_f32_e32 v9, v108, v124
	v_fmac_f32_e32 v7, v9, v84
	v_mul_f32_e32 v9, v116, v124
	v_fmac_f32_e32 v8, v9, v84
	v_mul_f32_e32 v9, v93, v125
	v_fmac_f32_e32 v5, v9, v85
	v_mul_f32_e32 v9, v101, v125
	v_fmac_f32_e32 v6, v9, v85
	v_mul_f32_e32 v9, v109, v125
	v_fmac_f32_e32 v7, v9, v85
	v_mul_f32_e32 v9, v117, v125
	v_fmac_f32_e32 v8, v9, v85
	v_cvt_pk_bf16_f32 v10, v5, v6
	v_cvt_pk_bf16_f32 v11, v7, v8
	global_store_dwordx2 v3, v[10:11], s[18:19]
	s_add_i32 s26, s26, s27
	s_branch .Lpw_task
; __device__ __forceinline__ void p0_prologue(const Params& p, LAS unsigned char* lds, const int wave_s) {
;     ...
;     float* cosT = (float*)(ws + WS_COS); float* sinT = (float*)(ws + WS_SIN);
;     for (int o = gt; o < 8192 * 32; o += GT) {
;         const int s = o >> 5, i = o & 31;
;         const float inv = exp2f(-(float)i * (13.287712379549449f / 32.0f));
;         const float ang = (float)s * inv;
;         const double rev = (double)ang * 0.15915494309189535; const float fr = (float)(rev - __builtin_rint(rev));
;         cosT[o] = __builtin_amdgcn_cosf(fr); sinT[o] = __builtin_amdgcn_sinf(fr);
.Lpw_done:
.LBB0_185:
	s_or_b64 exec, exec, s[2:3]
	s_mov_b32 s2, 0x40000
	v_cmp_gt_i32_e32 vcc, s2, v44
	v_ashrrev_i32_e32 v45, 31, v44
	s_and_saveexec_b64 s[2:3], vcc
	s_cbranch_execz .LBB0_188
	v_and_b32_e32 v1, 31, v1
	v_cvt_f32_ubyte0_e32 v1, v1
	v_mul_f32_e32 v2, 0xbed49a78, v1
	s_mov_b32 s4, 0xc2fc0000
	v_mov_b32_e32 v3, 0x42800000
	v_cmp_gt_f32_e32 vcc, s4, v2
	s_mov_b64 s[4:5], 0x1700000
	s_ashr_i32 s23, s22, 31
	v_cndmask_b32_e32 v2, 0, v3, vcc
	v_fmac_f32_e32 v2, 0xbed49a78, v1
	v_exp_f32_e32 v1, v2
	v_not_b32_e32 v2, 63
	v_cndmask_b32_e32 v2, 0, v2, vcc
	s_mov_b32 s10, 0x6dc9c883
	v_ldexp_f32 v1, v1, v2
	v_lshl_add_u64 v[2:3], v[44:45], 2, s[80:81]
	v_lshl_add_u64 v[2:3], v[2:3], 0, s[4:5]
	s_lshl_b64 s[4:5], s[22:23], 2
	s_mov_b64 s[8:9], 0
	s_mov_b32 s11, 0x3fc45f30
	s_mov_b32 s12, 0x3ffff
	v_mov_b32_e32 v4, v44
